# mixer_out group-norm reductions via DPP adds instead of 64 serialized ds_bpermute round trips (same association)
# speedup vs baseline: 1.0102x; 1.0040x over previous
; #define LAS __attribute__((address_space(3)))
; __device__ __forceinline__ void mixer_out_phase(const Ctx& X, LAS unsigned char* lds, int layer, int tid, int wave, int lane) {
;     ...
;     for (int u = blockIdx.x; u < 1536; u += gridDim.x) {
;         asm volatile("" : "+v"(lane), "+v"(tid));
;         LAS bf16_t* GT = opq((LAS bf16_t*)lds);
;         const int r = lane & 15, q = lane >> 4, h = wave >> 1, half = wave & 1;
;         const int mixer = u >> 9, rem = u & 511, b = rem >> 7, c = rem & 127;
;         const int uid = unit_id(mixer, b, h, c);
;         const int goff = mixer == 0 ? C_RG : (mixer == 1 ? C_GG : C_HG), moff = mixer == 0 ? 0 : (mixer == 1 ? 512 : 768);
;         const size_t row0 = (size_t)b * T + c * 64;
;         u32x4 gv[4];
; #pragma unroll
;         for (int n = 0; n < 4; ++n) { const int idx = tid + 512 * n; gv[n] = *(const u32x4*)(proj + (row0 + (idx >> 5)) * LDP + goff + (idx & 31) * 8); }
;         const bf16_t* qe = WSP(const bf16_t, WS_QEFF) + (size_t)uid * 4096;
;         const bf16_t* st = WSP(const bf16_t, WS_BCS) + (size_t)uid * 4096;
;         bf16x8 a[2][2], bb[4][2]; u32x4 ov[2][2];
; #pragma unroll
;         for (int rt = 0; rt < 2; ++rt) { const int rt4 = 2 * half + rt;
; #pragma unroll
;             for (int ks = 0; ks < 2; ++ks) a[rt][ks] = *(const bf16x8*)(qe + (16 * rt4 + r) * 64 + ks * 32 + q * 8);
;             const u32x4* ol = (const u32x4*)(WSP(const bf16_t, WS_OLOC) + ((size_t)uid * 4 + rt4) * 1024 + lane * 16); ov[rt][0] = ol[0]; ov[rt][1] = ol[1]; }
; #pragma unroll
;         for (int ct = 0; ct < 4; ++ct)
; #pragma unroll
;             for (int ks = 0; ks < 2; ++ks) { const bf16_t* tb = st + (size_t)((ct * 4 + 2 * ks + (q >> 1)) * 64) * 4;
;                 const u32x2 lo = *(const u32x2*)(tb + ((2 * (q & 1)) * 16 + r) * 4), hi = *(const u32x2*)(tb + ((2 * (q & 1) + 1) * 16 + r) * 4);
;                 bb[ct][ks] = __builtin_bit_cast(bf16x8, (u32x4){lo.x, lo.y, hi.x, hi.y}); }
;         const float* nw = mixer == 0 ? X.in[3] + layer * 256 + h * 64 : (mixer == 1 ? X.in[11] + layer * 64 : X.in[13] + layer * 64);
;         float wv[4];
; #pragma unroll
;         for (int ct = 0; ct < 4; ++ct) wv[ct] = nw[16 * ct + r];
; #pragma unroll
;         for (int n = 0; n < 4; ++n) { const int idx = tid + 512 * n; *(LAS u32x4*)(GT + (idx >> 5) * GP + (idx & 31) * 8) = gv[n]; }
;         LBAR();
.LBB0_888:
	s_ashr_i32 s6, s10, 9
	s_cmp_eq_u32 s6, 1
	s_movk_i32 s0, 0xd00
	s_cselect_b32 s7, 0x900, s0
	s_movk_i32 s0, 0x200
	s_cselect_b32 s11, s0, 0x300
	s_cselect_b32 s12, s50, s54
	s_cselect_b32 s13, s51, s55
	s_cmpk_lt_u32 s10, 0x200
	s_cselect_b64 s[0:1], -1, 0
	s_and_b64 s[0:1], s[0:1], exec
	s_cselect_b32 s11, 0, s11
	s_add_u32 s12, s12, s4
	s_addc_u32 s13, s13, s5
	s_cmpk_lt_u32 s10, 0x200
	s_cselect_b64 vcc, -1, 0
	s_and_b64 s[0:1], vcc, exec
	s_cselect_b32 s7, 0x300, s7
	s_cselect_b32 s1, s9, s13
	s_cselect_b32 s0, s8, s12
	s_bfe_u32 s12, s10, 0x20007
	s_and_b32 s13, s10, 0x7f
	s_lshl_b32 s14, s12, 9
	s_lshl_b32 s15, s6, 11
	s_lshl_b32 s6, s12, 13
	s_lshl_b32 s12, s13, 6
	s_or_b32 s16, s6, s12
	s_lshl_b32 s6, s7, 1
	s_add_u32 s6, s76, s6
	s_waitcnt vmcnt(0)
	v_lshlrev_b32_e32 v6, 4, v104
	v_ashrrev_i32_e32 v94, 5, v104
	s_addc_u32 s7, s77, 0
	v_and_b32_e32 v156, 0x1f0, v6
	v_ashrrev_i32_e32 v95, 31, v94
	v_lshl_add_u64 v[6:7], s[6:7], 0, v[156:157]
	v_lshl_add_u64 v[92:93], s[16:17], 0, v[94:95]
	v_mov_b32_e32 v108, v157
	v_mad_i64_i32 v[8:9], s[6:7], v92, s71, v[6:7]
	global_load_dwordx4 v[62:65], v[8:9], off
	v_add_u32_e32 v8, 0x200, v104
	v_ashrrev_i32_e32 v98, 5, v8
	v_ashrrev_i32_e32 v99, 31, v98
	v_lshl_add_u64 v[90:91], s[16:17], 0, v[98:99]
	v_mad_i64_i32 v[8:9], s[6:7], v90, s71, v[6:7]
	global_load_dwordx4 v[74:77], v[8:9], off
	v_add_u32_e32 v8, 0x400, v104
	v_ashrrev_i32_e32 v100, 5, v8
	v_ashrrev_i32_e32 v101, 31, v100
	v_lshl_add_u64 v[88:89], s[16:17], 0, v[100:101]
	v_mad_i64_i32 v[8:9], s[6:7], v88, s71, v[6:7]
	global_load_dwordx4 v[78:81], v[8:9], off
	v_add_u32_e32 v8, 0x600, v104
	v_ashrrev_i32_e32 v102, 5, v8
	v_ashrrev_i32_e32 v103, 31, v102
	v_lshl_add_u64 v[86:87], s[16:17], 0, v[102:103]
	v_mad_i64_i32 v[6:7], s[6:7], v86, s71, v[6:7]
	s_or_b32 s6, s13, s23
	s_add_i32 s6, s6, s15
	s_add_i32 s6, s6, s14
	s_ashr_i32 s7, s6, 31
	s_waitcnt vmcnt(14)
	v_ashrrev_i32_e32 v110, 4, v105
	s_lshl_b64 s[6:7], s[6:7], 13
	global_load_dwordx4 v[82:85], v[6:7], off
	s_add_u32 s12, s89, s6
	v_lshlrev_b32_e32 v6, 3, v110
	s_addc_u32 s13, s78, s7
	v_ashrrev_i32_e32 v7, 31, v6
	v_and_b32_e32 v109, 15, v105
	v_lshl_add_u64 v[6:7], v[6:7], 1, s[12:13]
	s_add_u32 s12, s19, s6
	s_addc_u32 s13, s20, s7
	s_lshl_b32 s16, s21, 1
	v_lshlrev_b32_e32 v22, 7, v110
	v_lshlrev_b32_e32 v95, 2, v109
	s_add_u32 s6, s74, s6
	v_and_or_b32 v22, v22, s33, v95
	s_addc_u32 s7, s75, s7
	v_lshlrev_b32_e32 v22, 1, v22
	v_mov_b32_e32 v23, v157
	v_lshlrev_b32_e32 v12, 6, v109
	v_lshlrev_b32_e32 v8, 4, v105
	v_lshl_add_u64 v[50:51], s[6:7], 0, v[22:23]
	v_lshlrev_b32_e32 v22, 1, v105
	v_ashrrev_i32_e32 v9, 31, v8
	v_or_b32_e32 v10, s21, v12
	v_and_b32_e32 v52, 0xffffffc0, v22
	v_lshl_add_u64 v[8:9], v[8:9], 1, s[12:13]
	v_lshlrev_b32_e32 v10, 1, v10
	v_mov_b32_e32 v11, v157
	v_add_u32_e32 v26, 0x80, v52
	v_add_u32_e32 v30, 0x100, v52
	v_lshl_add_u64 v[10:11], v[6:7], 0, v[10:11]
	v_lshl_add_u64 v[18:19], v[8:9], 0, s[16:17]
	v_add_lshl_u32 v8, v12, s21, 1
	v_mov_b32_e32 v9, v157
	v_ashrrev_i32_e32 v53, 31, v52
	v_ashrrev_i32_e32 v27, 31, v26
	v_ashrrev_i32_e32 v31, 31, v30
	global_load_dwordx4 v[66:69], v[10:11], off
	global_load_dwordx4 v[70:73], v[10:11], off offset:64
	global_load_dwordx4 v[54:57], v[18:19], off offset:16
	global_load_dwordx4 v[58:61], v[18:19], off
	v_lshl_add_u64 v[10:11], v[6:7], 0, v[8:9]
	s_waitcnt vmcnt(12)
	v_lshl_add_u64 v[24:25], v[52:53], 3, v[50:51]
	v_lshl_add_u64 v[28:29], v[26:27], 3, v[50:51]
	v_lshl_add_u64 v[32:33], v[30:31], 3, v[50:51]
	global_load_dwordx4 v[6:9], v[10:11], off offset:2048
	s_nop 0
	global_load_dwordx4 v[10:13], v[10:11], off offset:2112
	s_nop 0
	global_load_dwordx4 v[14:17], v[18:19], off offset:2064
	s_nop 0
	global_load_dwordx4 v[18:21], v[18:19], off offset:2048
	s_nop 0
	global_load_dwordx2 v[22:23], v[24:25], off
	s_nop 0
	global_load_dwordx2 v[24:25], v[24:25], off offset:128
	s_nop 0
	global_load_dwordx2 v[26:27], v[28:29], off
	s_nop 0
	global_load_dwordx2 v[28:29], v[28:29], off offset:128
	s_nop 0
	global_load_dwordx2 v[30:31], v[32:33], off
	s_nop 0
	global_load_dwordx2 v[32:33], v[32:33], off offset:128
	v_add_u32_e32 v34, 0x180, v52
	v_add_u32_e32 v38, 0x200, v52
	v_add_u32_e32 v42, 0x280, v52
	v_add_u32_e32 v46, 0x300, v52
	v_ashrrev_i32_e32 v35, 31, v34
	v_ashrrev_i32_e32 v39, 31, v38
	v_ashrrev_i32_e32 v43, 31, v42
	v_ashrrev_i32_e32 v47, 31, v46
	v_lshl_add_u64 v[36:37], v[34:35], 3, v[50:51]
	v_lshl_add_u64 v[40:41], v[38:39], 3, v[50:51]
	v_lshl_add_u64 v[44:45], v[42:43], 3, v[50:51]
	v_lshl_add_u64 v[48:49], v[46:47], 3, v[50:51]
	global_load_dwordx2 v[34:35], v[36:37], off
	s_nop 0
	global_load_dwordx2 v[36:37], v[36:37], off offset:128
	s_nop 0
	global_load_dwordx2 v[38:39], v[40:41], off
	s_nop 0
	global_load_dwordx2 v[40:41], v[40:41], off offset:128
	s_nop 0
	global_load_dwordx2 v[42:43], v[44:45], off
	s_nop 0
	global_load_dwordx2 v[44:45], v[44:45], off offset:128
	s_nop 0
	global_load_dwordx2 v[46:47], v[48:49], off
	s_nop 0
	global_load_dwordx2 v[48:49], v[48:49], off offset:128
	v_add_u32_e32 v52, 0x380, v52
	v_ashrrev_i32_e32 v53, 31, v52
	v_lshl_add_u64 v[52:53], v[52:53], 3, v[50:51]
	global_load_dwordx2 v[50:51], v[52:53], off
	s_nop 0
	global_load_dwordx2 v[52:53], v[52:53], off offset:128
	v_add_u32_e32 v112, v108, v156
	global_load_dword v106, v95, s[0:1]
	global_load_dword v103, v95, s[0:1] offset:64
	global_load_dword v101, v95, s[0:1] offset:128
	global_load_dword v99, v95, s[0:1] offset:192
	v_mad_u64_u32 v[96:97], s[0:1], v94, s34, v[112:113]
	s_waitcnt vmcnt(31)
	ds_write_b128 v96, v[62:65]
	v_mad_u64_u32 v[94:95], s[0:1], v98, s34, v[112:113]
	v_and_b32_e32 v63, 64, v230
	s_waitcnt vmcnt(30)
	ds_write_b128 v94, v[74:77]
	v_mad_u64_u32 v[76:77], s[0:1], v100, s34, v[112:113]
	v_mad_u64_u32 v[74:75], s[0:1], v102, s34, v[112:113]
	v_xor_b32_e32 v62, 1, v230
	v_add_u32_e32 v63, 64, v63
	v_cmp_lt_i32_e64 s[0:1], v62, v63
	s_waitcnt vmcnt(29)
	ds_write_b128 v76, v[78:81]
	s_waitcnt vmcnt(28)
	ds_write_b128 v74, v[82:85]
	v_cndmask_b32_e64 v62, v230, v62, s[0:1]
	v_lshlrev_b32_e32 v75, 2, v62
	v_xor_b32_e32 v62, 2, v230
	v_cmp_lt_i32_e64 s[0:1], v62, v63
	v_lshl_add_u32 v84, v110, 2, s22
	v_add_u32_e32 v85, s23, v108
	v_cndmask_b32_e64 v62, v230, v62, s[0:1]
	v_lshlrev_b32_e32 v77, 2, v62
	v_xor_b32_e32 v62, 4, v230
	v_cmp_lt_i32_e64 s[0:1], v62, v63
	v_lshlrev_b32_e32 v95, 1, v109
	v_cndmask_b32_e32 v107, v225, v229, vcc
	v_cndmask_b32_e64 v62, v230, v62, s[0:1]
	v_lshlrev_b32_e32 v78, 2, v62
	v_xor_b32_e32 v62, 8, v230
	v_cmp_lt_i32_e64 s[0:1], v62, v63
	s_waitcnt lgkmcnt(0)
	s_barrier
; #define LAS __attribute__((address_space(3)))
; __device__ __forceinline__ float bf_lo(unsigned u) { return __uint_as_float(u << 16); }
; __device__ __forceinline__ float bf_hi(unsigned u) { return __uint_as_float(u & 0xffff0000u); }
; __device__ __forceinline__ float bf2f(bf16_t b) { return __uint_as_float((unsigned)b << 16); }
; __device__ __forceinline__ bf16_t f2bf(float f) { return (bf16_t)(pk2(f, 0.f) & 0xffffu); }
; __device__ __forceinline__ float silu_acc(float x) { return x * frcp(1.0f + fexp(-x)); }
; __device__ __forceinline__ void mixer_out_phase(const Ctx& X, LAS unsigned char* lds, int layer, int tid, int wave, int lane) {
;     ...
;         for (int rt = 0; rt < 2; ++rt) {
;             f32x4 acc[4];
;             acc[0] = (f32x4){bf_lo(ov[rt][0].x), bf_hi(ov[rt][0].x), bf_lo(ov[rt][0].y), bf_hi(ov[rt][0].y)}; acc[1] = (f32x4){bf_lo(ov[rt][0].z), bf_hi(ov[rt][0].z), bf_lo(ov[rt][0].w), bf_hi(ov[rt][0].w)};
;             acc[2] = (f32x4){bf_lo(ov[rt][1].x), bf_hi(ov[rt][1].x), bf_lo(ov[rt][1].y), bf_hi(ov[rt][1].y)}; acc[3] = (f32x4){bf_lo(ov[rt][1].z), bf_hi(ov[rt][1].z), bf_lo(ov[rt][1].w), bf_hi(ov[rt][1].w)};
; #pragma unroll
;             for (int ct = 0; ct < 4; ++ct)
; #pragma unroll
;                 for (int ks = 0; ks < 2; ++ks) acc[ct] = __builtin_amdgcn_mfma_f32_16x16x32_bf16(a[rt][ks], bb[ct][ks], acc[ct], 0, 0, 0);
; #pragma unroll
;             for (int j = 0; j < 4; ++j) {
;                 float sm = (acc[0][j] + acc[1][j]) + (acc[2][j] + acc[3][j]);
;                 sm += __shfl_xor(sm, 1); sm += __shfl_xor(sm, 2); sm += __shfl_xor(sm, 4); sm += __shfl_xor(sm, 8);
;                 const float mu = mixer == 0 ? sm * (1.f / 64.f) : 0.f;
;                 float d[4], s2 = 0.f;
; #pragma unroll
;                 for (int ct = 0; ct < 4; ++ct) { d[ct] = acc[ct][j] - mu; s2 += d[ct] * d[ct]; }
;                 s2 += __shfl_xor(s2, 1); s2 += __shfl_xor(s2, 2); s2 += __shfl_xor(s2, 4); s2 += __shfl_xor(s2, 8);
;                 const float rs = rsqrtf(s2 * (1.f / 64.f) + (mixer == 0 ? 1e-5f : 1e-6f));
;                 const int ii = 16 * (2 * half + rt) + 4 * q + j;
; #pragma unroll
;                 for (int ct = 0; ct < 4; ++ct) { LAS bf16_t* gp = GT + ii * GP + h * 64 + 16 * ct + r;
;                     const float y = d[ct] * rs * wv[ct] * silu_acc(bf2f(*gp));
;                     *gp = on ? f2bf(y) : (bf16_t)0; }
	s_waitcnt vmcnt(25)
	v_lshlrev_b32_e32 v80, 16, v54
	v_cndmask_b32_e64 v62, v230, v62, s[0:1]
	v_lshlrev_b32_e32 v79, 2, v62
	s_waitcnt vmcnt(24)
	v_lshlrev_b32_e32 v62, 16, v58
	v_and_b32_e32 v63, 0xffff0000, v58
	v_lshlrev_b32_e32 v64, 16, v59
	v_and_b32_e32 v65, 0xffff0000, v59
	v_lshlrev_b32_e32 v58, 16, v60
	v_and_b32_e32 v59, 0xffff0000, v60
	v_lshlrev_b32_e32 v60, 16, v61
	v_and_b32_e32 v61, 0xffff0000, v61
	v_and_b32_e32 v81, 0xffff0000, v54
	v_lshlrev_b32_e32 v82, 16, v55
	s_waitcnt vmcnt(14)
	v_mfma_f32_16x16x32_bf16 v[58:61], v[66:69], v[30:33], v[58:61]
	v_and_b32_e32 v83, 0xffff0000, v55
	v_lshlrev_b32_e32 v108, 16, v56
	v_and_b32_e32 v109, 0xffff0000, v56
	v_lshlrev_b32_e32 v110, 16, v57
	v_and_b32_e32 v111, 0xffff0000, v57
	v_mfma_f32_16x16x32_bf16 v[54:57], v[66:69], v[22:25], v[62:65]
	s_waitcnt vmcnt(12)
	v_mfma_f32_16x16x32_bf16 v[62:65], v[70:73], v[34:37], v[58:61]
	s_waitcnt vmcnt(10)
	v_mfma_f32_16x16x32_bf16 v[58:61], v[66:69], v[38:41], v[80:83]
	s_waitcnt vmcnt(6)
	v_mfma_f32_16x16x32_bf16 v[66:69], v[66:69], v[46:49], v[108:111]
	v_mfma_f32_16x16x32_bf16 v[54:57], v[70:73], v[26:29], v[54:57]
	v_mfma_f32_16x16x32_bf16 v[58:61], v[70:73], v[42:45], v[58:61]
	s_waitcnt vmcnt(4)
	v_mfma_f32_16x16x32_bf16 v[66:69], v[70:73], v[50:53], v[66:69]
	s_nop 4
	v_mov_b32_e32 v70, v54
	v_mov_b32_e32 v71, v58
	v_mov_b32_e32 v72, v62
	v_mov_b32_e32 v83, v58
	v_mov_b32_e32 v73, v66
	v_pk_add_f32 v[70:71], v[70:71], v[72:73]
	v_mov_b32_e32 v72, v54
	v_add_f32_e32 v70, v70, v71
	s_nop 1
	v_mov_b32_e32 v73, v62
	v_mov_b32_e32 v82, v66
	s_waitcnt lgkmcnt(0)
	v_add_f32_dpp v70, v70, v70 quad_perm:[1,0,3,2] row_mask:0xf bank_mask:0xf
	s_nop 1
	s_waitcnt lgkmcnt(0)
	v_add_f32_dpp v70, v70, v70 quad_perm:[2,3,0,1] row_mask:0xf bank_mask:0xf
	s_nop 1
	s_waitcnt lgkmcnt(0)
	v_add_f32_dpp v70, v70, v70 row_half_mirror row_mask:0xf bank_mask:0xf
	s_nop 1
	s_waitcnt lgkmcnt(0)
	v_add_f32_dpp v70, v70, v70 row_mirror row_mask:0xf bank_mask:0xf
	v_mul_f32_e32 v70, 0x3c800000, v70
	v_cndmask_b32_e32 v70, 0, v70, vcc
	v_pk_add_f32 v[72:73], v[72:73], v[70:71] op_sel_hi:[1,0] neg_lo:[0,1] neg_hi:[0,1]
	v_pk_add_f32 v[70:71], v[82:83], v[70:71] op_sel_hi:[1,0] neg_lo:[0,1] neg_hi:[0,1]
	v_pk_mul_f32 v[80:81], v[72:73], v[72:73]
	v_pk_mul_f32 v[82:83], v[70:71], v[70:71]
	v_add_f32_e32 v54, v80, v81
	v_add_f32_e32 v54, v83, v54
	v_add_f32_e32 v54, v82, v54
	s_nop 1
	s_waitcnt lgkmcnt(0)
	v_add_f32_dpp v54, v54, v54 quad_perm:[1,0,3,2] row_mask:0xf bank_mask:0xf
	s_nop 1
	s_waitcnt lgkmcnt(0)
	v_add_f32_dpp v54, v54, v54 quad_perm:[2,3,0,1] row_mask:0xf bank_mask:0xf
	s_nop 1
	s_waitcnt lgkmcnt(0)
	v_add_f32_dpp v54, v54, v54 row_half_mirror row_mask:0xf bank_mask:0xf
	s_nop 1
	s_waitcnt lgkmcnt(0)
	v_add_f32_dpp v54, v54, v54 row_mirror row_mask:0xf bank_mask:0xf
	v_fmamk_f32 v54, v54, 0x3c800000, v107
	v_cmp_gt_f32_e64 s[0:1], s3, v54
	v_mul_f32_e32 v58, 0x4b800000, v54
	s_nop 0
	v_cndmask_b32_e64 v54, v54, v58, s[0:1]
	v_rsq_f32_e32 v54, v54
	s_nop 0
	v_mul_f32_e32 v58, 0x45800000, v54
	v_cndmask_b32_e64 v58, v54, v58, s[0:1]
	v_mul_lo_u32 v54, v84, s34
	v_add3_u32 v54, v85, v95, v54
	ds_read_u16 v62, v54
	s_waitcnt lgkmcnt(0)
	v_lshlrev_b32_e32 v62, 16, v62
	v_mul_f32_e32 v66, 0xbfb8aa3b, v62
	v_exp_f32_e32 v66, v66
	s_nop 0
	v_add_f32_e32 v66, 1.0, v66
	v_rcp_f32_e32 v66, v66
	s_nop 0
	v_mul_f32_e32 v62, v66, v62
	v_mul_f32_e32 v66, v72, v58
	s_waitcnt vmcnt(3)
	v_mul_f32_e32 v66, v106, v66
	v_mul_f32_e32 v62, v62, v66
	v_cvt_pk_bf16_f32 v62, v62, v157
	ds_write_b16 v54, v62
	ds_read_u16 v62, v54 offset:32
	s_waitcnt lgkmcnt(0)
	v_lshlrev_b32_e32 v62, 16, v62
	v_mul_f32_e32 v66, 0xbfb8aa3b, v62
	v_exp_f32_e32 v66, v66
	s_nop 0
	v_add_f32_e32 v66, 1.0, v66
	v_rcp_f32_e32 v66, v66
	s_nop 0
	v_mul_f32_e32 v62, v66, v62
	v_mul_f32_e32 v66, v73, v58
	s_waitcnt vmcnt(2)
	v_mul_f32_e32 v66, v103, v66
	v_mul_f32_e32 v62, v62, v66
	v_cvt_pk_bf16_f32 v62, v62, v157
	ds_write_b16 v54, v62 offset:32
	ds_read_u16 v62, v54 offset:64
	s_waitcnt lgkmcnt(0)
	v_lshlrev_b32_e32 v62, 16, v62
	v_mul_f32_e32 v66, 0xbfb8aa3b, v62
	v_exp_f32_e32 v66, v66
	s_nop 0
	v_add_f32_e32 v66, 1.0, v66
	v_rcp_f32_e32 v66, v66
	s_nop 0
	v_mul_f32_e32 v62, v66, v62
	v_mul_f32_e32 v66, v71, v58
	s_waitcnt vmcnt(1)
	v_mul_f32_e32 v66, v101, v66
	v_mul_f32_e32 v62, v62, v66
	v_cvt_pk_bf16_f32 v62, v62, v157
	ds_write_b16 v54, v62 offset:64
	ds_read_u16 v62, v54 offset:96
	v_mul_f32_e32 v58, v70, v58
	s_waitcnt vmcnt(0)
	s_add_i32 s98, s10, s18
	s_cmpk_ge_u32 s98, 0x600
	s_cbranch_scc1 .LpfO_done
	s_lshr_b32 s99, s98, 9
	s_and_b32 s98, s98, 0x1ff
	s_lshr_b32 s100, s98, 7
	s_and_b32 s98, s98, 0x7f
	s_lshl_b32 s101, s99, 2
	s_add_u32 s101, s101, s100
	s_lshl_b32 s101, s101, 9
	s_add_u32 s101, s101, s98
	s_lshl_b32 s101, s101, 13
	s_cmp_eq_u32 s99, 2
	s_mul_i32 s99, s99, 0xc00
	s_cselect_b32 s32, 0x400, 0
	s_sub_u32 s99, s99, s32
	s_add_u32 s99, s99, 0x600
	s_lshl_b32 s100, s100, 13
	s_lshl_b32 s98, s98, 6
	s_add_u32 s98, s98, s100
	s_mul_i32 s98, s98, 0x1c00
	s_add_u32 s98, s98, s99
	v_and_b32_e32 v237, 0xff, v224
	v_lshrrev_b32_e32 v238, 2, v237
	v_and_b32_e32 v239, 3, v237
	v_lshlrev_b32_e32 v239, 7, v239
	v_mad_u32_u24 v238, v238, s71, v239
	v_lshrrev_b32_e32 v239, 6, v237
	v_and_b32_e32 v237, 63, v237
	v_lshlrev_b32_e32 v239, 20, v239
	v_lshl_or_b32 v237, v237, 7, v239
	v_readfirstlane_b32 s32, v224
	s_add_u32 s82, s76, s98
	s_addc_u32 s83, s77, 0
	s_cmpk_lt_u32 s32, 0x100
	s_cbranch_scc0 .LpfO_hi
	s_add_u32 s98, s101, 0x3500000
	s_add_u32 s98, s30, s98
	s_addc_u32 s99, s31, 0
	global_load_dword v234, v238, s[82:83]
	global_load_dword v234, v237, s[98:99]
	s_branch .LpfO_done

; #define LAS __attribute__((address_space(3)))
; __device__ __forceinline__ float bf2f(bf16_t b) { return __uint_as_float((unsigned)b << 16); }
; __device__ __forceinline__ bf16_t f2bf(float f) { return (bf16_t)(pk2(f, 0.f) & 0xffffu); }
; __device__ __forceinline__ float silu_acc(float x) { return x * frcp(1.0f + fexp(-x)); }
; __device__ __forceinline__ void mixer_out_phase(const Ctx& X, LAS unsigned char* lds, int layer, int tid, int wave, int lane) {
;     ...
;             for (int j = 0; j < 4; ++j) {
;                 float sm = (acc[0][j] + acc[1][j]) + (acc[2][j] + acc[3][j]);
;                 sm += __shfl_xor(sm, 1); sm += __shfl_xor(sm, 2); sm += __shfl_xor(sm, 4); sm += __shfl_xor(sm, 8);
;                 const float mu = mixer == 0 ? sm * (1.f / 64.f) : 0.f;
;                 float d[4], s2 = 0.f;
; #pragma unroll
;                 for (int ct = 0; ct < 4; ++ct) { d[ct] = acc[ct][j] - mu; s2 += d[ct] * d[ct]; }
;                 s2 += __shfl_xor(s2, 1); s2 += __shfl_xor(s2, 2); s2 += __shfl_xor(s2, 4); s2 += __shfl_xor(s2, 8);
;                 const float rs = rsqrtf(s2 * (1.f / 64.f) + (mixer == 0 ? 1e-5f : 1e-6f));
;                 const int ii = 16 * (2 * half + rt) + 4 * q + j;
; #pragma unroll
;                 for (int ct = 0; ct < 4; ++ct) { LAS bf16_t* gp = GT + ii * GP + h * 64 + 16 * ct + r;
;                     const float y = d[ct] * rs * wv[ct] * silu_acc(bf2f(*gp));
;                     *gp = on ? f2bf(y) : (bf16_t)0; }
.LpfO_done:
	v_mul_f32_e32 v58, v99, v58
	s_waitcnt lgkmcnt(0)
	v_lshlrev_b32_e32 v62, 16, v62
	v_mul_f32_e32 v66, 0xbfb8aa3b, v62
	v_exp_f32_e32 v66, v66
	s_nop 0
	v_add_f32_e32 v66, 1.0, v66
	v_rcp_f32_e32 v66, v66
	s_nop 0
	v_mul_f32_e32 v62, v66, v62
	v_mul_f32_e32 v58, v62, v58
	v_cvt_pk_bf16_f32 v58, v58, v157
	ds_write_b16 v54, v58 offset:96
	v_mov_b32_e32 v58, v55
	v_mov_b32_e32 v66, v63
	v_pk_add_f32 v[70:71], v[58:59], v[66:67]
	s_nop 0
	v_add_f32_e32 v58, v70, v71
	s_nop 1
	s_waitcnt lgkmcnt(0)
	v_add_f32_dpp v58, v58, v58 quad_perm:[1,0,3,2] row_mask:0xf bank_mask:0xf
	s_nop 1
	s_waitcnt lgkmcnt(0)
	v_add_f32_dpp v58, v58, v58 quad_perm:[2,3,0,1] row_mask:0xf bank_mask:0xf
	s_nop 1
	s_waitcnt lgkmcnt(0)
	v_add_f32_dpp v58, v58, v58 row_half_mirror row_mask:0xf bank_mask:0xf
	s_nop 1
	s_waitcnt lgkmcnt(0)
	v_add_f32_dpp v58, v58, v58 row_mirror row_mask:0xf bank_mask:0xf
	v_mul_f32_e32 v58, 0x3c800000, v58
	v_cndmask_b32_e32 v66, 0, v58, vcc
	v_mov_b32_e32 v62, v55
	v_pk_add_f32 v[62:63], v[62:63], v[66:67] op_sel_hi:[1,0] neg_lo:[0,1] neg_hi:[0,1]
	v_mov_b32_e32 v58, v67
	v_pk_mul_f32 v[70:71], v[62:63], v[62:63]
	v_pk_add_f32 v[58:59], v[58:59], v[66:67] op_sel_hi:[1,0] neg_lo:[0,1] neg_hi:[0,1]
	v_add_f32_e32 v55, v70, v71
	v_pk_mul_f32 v[66:67], v[58:59], v[58:59]
	v_mov_b32_e32 v70, v68
	v_add_f32_e32 v55, v67, v55
	v_add_f32_e32 v55, v66, v55
	s_nop 1
	v_mov_b32_e32 v71, v60
	s_waitcnt lgkmcnt(0)
	v_add_f32_dpp v55, v55, v55 quad_perm:[1,0,3,2] row_mask:0xf bank_mask:0xf
	s_nop 1
	s_waitcnt lgkmcnt(0)
	v_add_f32_dpp v55, v55, v55 quad_perm:[2,3,0,1] row_mask:0xf bank_mask:0xf
	s_nop 1
	s_waitcnt lgkmcnt(0)
	v_add_f32_dpp v55, v55, v55 row_half_mirror row_mask:0xf bank_mask:0xf
	s_nop 1
	s_waitcnt lgkmcnt(0)
	v_add_f32_dpp v55, v55, v55 row_mirror row_mask:0xf bank_mask:0xf
	v_fmamk_f32 v55, v55, 0x3c800000, v107
	v_cmp_gt_f32_e64 s[0:1], s3, v55
	v_mul_f32_e32 v66, 0x4b800000, v55
	s_nop 0
	v_cndmask_b32_e64 v55, v55, v66, s[0:1]
	v_rsq_f32_e32 v55, v55
	s_nop 0
	v_mul_f32_e32 v66, 0x45800000, v55
	v_cndmask_b32_e64 v55, v55, v66, s[0:1]
	ds_read_u16 v66, v54 offset:528
	v_mul_f32_e32 v62, v62, v55
	v_mul_f32_e32 v62, v106, v62
	v_mul_f32_e32 v63, v63, v55
	v_mul_f32_e32 v63, v103, v63
	s_waitcnt lgkmcnt(0)
	v_lshlrev_b32_e32 v66, 16, v66
	v_mul_f32_e32 v67, 0xbfb8aa3b, v66
	v_exp_f32_e32 v67, v67
	v_mul_f32_e32 v59, v59, v55
	v_mul_f32_e32 v59, v101, v59
	v_mul_f32_e32 v55, v58, v55
	v_add_f32_e32 v67, 1.0, v67
	v_rcp_f32_e32 v67, v67
	v_mul_f32_e32 v55, v99, v55
	v_mov_b32_e32 v58, v56
	v_mul_f32_e32 v66, v67, v66
	v_mul_f32_e32 v62, v66, v62
	v_cvt_pk_bf16_f32 v62, v62, v157
	ds_write_b16 v54, v62 offset:528
	ds_read_u16 v62, v54 offset:560
	s_waitcnt lgkmcnt(0)
	v_lshlrev_b32_e32 v62, 16, v62
	v_mul_f32_e32 v66, 0xbfb8aa3b, v62
	v_exp_f32_e32 v66, v66
	s_nop 0
	v_add_f32_e32 v66, 1.0, v66
	v_rcp_f32_e32 v66, v66
	s_nop 0
	v_mul_f32_e32 v62, v66, v62
	v_mul_f32_e32 v62, v62, v63
	v_cvt_pk_bf16_f32 v62, v62, v157
	ds_write_b16 v54, v62 offset:560
	ds_read_u16 v62, v54 offset:592
	s_waitcnt lgkmcnt(0)
	v_lshlrev_b32_e32 v62, 16, v62
	v_mul_f32_e32 v63, 0xbfb8aa3b, v62
	v_exp_f32_e32 v63, v63
	s_nop 0
	v_add_f32_e32 v63, 1.0, v63
	v_rcp_f32_e32 v63, v63
	s_nop 0
	v_mul_f32_e32 v62, v63, v62
	v_mul_f32_e32 v59, v62, v59
	v_cvt_pk_bf16_f32 v59, v59, v157
	ds_write_b16 v54, v59 offset:592
	ds_read_u16 v59, v54 offset:624
	v_mov_b32_e32 v63, v68
	v_mov_b32_e32 v68, v65
	s_waitcnt lgkmcnt(0)
	v_lshlrev_b32_e32 v59, 16, v59
	v_mul_f32_e32 v62, 0xbfb8aa3b, v59
	v_exp_f32_e32 v62, v62
	s_nop 0
	v_add_f32_e32 v62, 1.0, v62
	v_rcp_f32_e32 v62, v62
	s_nop 0
	v_mul_f32_e32 v59, v62, v59
	v_mul_f32_e32 v55, v55, v59
	v_mov_b32_e32 v59, v60
	v_mov_b32_e32 v62, v64
	v_cvt_pk_bf16_f32 v55, v55, v157
	v_pk_add_f32 v[58:59], v[58:59], v[62:63]
	ds_write_b16 v54, v55 offset:624
	v_add_f32_e32 v55, v58, v59
	s_nop 1
	v_mov_b32_e32 v62, v56
	v_mov_b32_e32 v63, v64
	v_mov_b32_e32 v64, v57
	s_waitcnt lgkmcnt(0)
	v_add_f32_dpp v55, v55, v55 quad_perm:[1,0,3,2] row_mask:0xf bank_mask:0xf
	s_nop 1
	s_waitcnt lgkmcnt(0)
	v_add_f32_dpp v55, v55, v55 quad_perm:[2,3,0,1] row_mask:0xf bank_mask:0xf
	s_nop 1
	s_waitcnt lgkmcnt(0)
	v_add_f32_dpp v55, v55, v55 row_half_mirror row_mask:0xf bank_mask:0xf
	s_nop 1
	s_waitcnt lgkmcnt(0)
	v_add_f32_dpp v55, v55, v55 row_mirror row_mask:0xf bank_mask:0xf
	v_mul_f32_e32 v55, 0x3c800000, v55
	v_cndmask_b32_e32 v58, 0, v55, vcc
	v_pk_add_f32 v[62:63], v[62:63], v[58:59] op_sel_hi:[1,0] neg_lo:[0,1] neg_hi:[0,1]
	v_pk_add_f32 v[58:59], v[70:71], v[58:59] op_sel_hi:[1,0] neg_lo:[0,1] neg_hi:[0,1]
	v_pk_mul_f32 v[66:67], v[62:63], v[62:63]
	v_pk_mul_f32 v[70:71], v[58:59], v[58:59]
	v_add_f32_e32 v55, v66, v67
	v_add_f32_e32 v55, v71, v55
	v_add_f32_e32 v55, v70, v55
	s_nop 1
	v_lshlrev_b32_e32 v66, 16, v17
	v_and_b32_e32 v67, 0xffff0000, v17
	s_waitcnt lgkmcnt(0)
	v_add_f32_dpp v55, v55, v55 quad_perm:[1,0,3,2] row_mask:0xf bank_mask:0xf
	s_nop 1
	s_waitcnt lgkmcnt(0)
	v_add_f32_dpp v55, v55, v55 quad_perm:[2,3,0,1] row_mask:0xf bank_mask:0xf
	s_nop 1
	s_waitcnt lgkmcnt(0)
	v_add_f32_dpp v55, v55, v55 row_half_mirror row_mask:0xf bank_mask:0xf
	s_nop 1
	s_waitcnt lgkmcnt(0)
	v_add_f32_dpp v55, v55, v55 row_mirror row_mask:0xf bank_mask:0xf
	v_fmamk_f32 v55, v55, 0x3c800000, v107
	v_cmp_gt_f32_e64 s[0:1], s3, v55
	v_mul_f32_e32 v56, 0x4b800000, v55
	s_nop 0
	v_cndmask_b32_e64 v55, v55, v56, s[0:1]
	v_rsq_f32_e32 v55, v55
	s_nop 0
	v_mul_f32_e32 v56, 0x45800000, v55
	v_cndmask_b32_e64 v55, v55, v56, s[0:1]
	ds_read_u16 v56, v54 offset:1056
	v_mul_f32_e32 v59, v59, v55
	v_mul_f32_e32 v59, v101, v59
	s_waitcnt lgkmcnt(0)
; #define LAS __attribute__((address_space(3)))
; __device__ __forceinline__ float bf_lo(unsigned u) { return __uint_as_float(u << 16); }
; __device__ __forceinline__ float bf_hi(unsigned u) { return __uint_as_float(u & 0xffff0000u); }
; __device__ __forceinline__ float bf2f(bf16_t b) { return __uint_as_float((unsigned)b << 16); }
; __device__ __forceinline__ bf16_t f2bf(float f) { return (bf16_t)(pk2(f, 0.f) & 0xffffu); }
; __device__ __forceinline__ float silu_acc(float x) { return x * frcp(1.0f + fexp(-x)); }
; __device__ __forceinline__ void mixer_out_phase(const Ctx& X, LAS unsigned char* lds, int layer, int tid, int wave, int lane) {
;     ...
;         for (int rt = 0; rt < 2; ++rt) {
;             f32x4 acc[4];
;             acc[0] = (f32x4){bf_lo(ov[rt][0].x), bf_hi(ov[rt][0].x), bf_lo(ov[rt][0].y), bf_hi(ov[rt][0].y)}; acc[1] = (f32x4){bf_lo(ov[rt][0].z), bf_hi(ov[rt][0].z), bf_lo(ov[rt][0].w), bf_hi(ov[rt][0].w)};
;             acc[2] = (f32x4){bf_lo(ov[rt][1].x), bf_hi(ov[rt][1].x), bf_lo(ov[rt][1].y), bf_hi(ov[rt][1].y)}; acc[3] = (f32x4){bf_lo(ov[rt][1].z), bf_hi(ov[rt][1].z), bf_lo(ov[rt][1].w), bf_hi(ov[rt][1].w)};
; #pragma unroll
;             for (int ct = 0; ct < 4; ++ct)
; #pragma unroll
;                 for (int ks = 0; ks < 2; ++ks) acc[ct] = __builtin_amdgcn_mfma_f32_16x16x32_bf16(a[rt][ks], bb[ct][ks], acc[ct], 0, 0, 0);
; #pragma unroll
;             for (int j = 0; j < 4; ++j) {
;                 float sm = (acc[0][j] + acc[1][j]) + (acc[2][j] + acc[3][j]);
;                 sm += __shfl_xor(sm, 1); sm += __shfl_xor(sm, 2); sm += __shfl_xor(sm, 4); sm += __shfl_xor(sm, 8);
;                 const float mu = mixer == 0 ? sm * (1.f / 64.f) : 0.f;
;                 float d[4], s2 = 0.f;
; #pragma unroll
;                 for (int ct = 0; ct < 4; ++ct) { d[ct] = acc[ct][j] - mu; s2 += d[ct] * d[ct]; }
;                 s2 += __shfl_xor(s2, 1); s2 += __shfl_xor(s2, 2); s2 += __shfl_xor(s2, 4); s2 += __shfl_xor(s2, 8);
;                 const float rs = rsqrtf(s2 * (1.f / 64.f) + (mixer == 0 ? 1e-5f : 1e-6f));
;                 const int ii = 16 * (2 * half + rt) + 4 * q + j;
; #pragma unroll
;                 for (int ct = 0; ct < 4; ++ct) { LAS bf16_t* gp = GT + ii * GP + h * 64 + 16 * ct + r;
;                     const float y = d[ct] * rs * wv[ct] * silu_acc(bf2f(*gp));
;                     *gp = on ? f2bf(y) : (bf16_t)0; }
	v_lshlrev_b32_e32 v56, 16, v56
	v_mul_f32_e32 v60, 0xbfb8aa3b, v56
	v_exp_f32_e32 v60, v60
	s_nop 0
	v_add_f32_e32 v60, 1.0, v60
	v_rcp_f32_e32 v60, v60
	s_nop 0
	v_mul_f32_e32 v56, v60, v56
	v_mul_f32_e32 v60, v62, v55
	v_mul_f32_e32 v60, v106, v60
	v_mul_f32_e32 v56, v56, v60
	v_cvt_pk_bf16_f32 v56, v56, v157
	ds_write_b16 v54, v56 offset:1056
	ds_read_u16 v56, v54 offset:1088
	s_waitcnt lgkmcnt(0)
	v_lshlrev_b32_e32 v56, 16, v56
	v_mul_f32_e32 v60, 0xbfb8aa3b, v56
	v_exp_f32_e32 v60, v60
	s_nop 0
	v_add_f32_e32 v60, 1.0, v60
	v_rcp_f32_e32 v60, v60
	s_nop 0
	v_mul_f32_e32 v56, v60, v56
	v_mul_f32_e32 v60, v63, v55
	v_mul_f32_e32 v60, v103, v60
	v_mul_f32_e32 v56, v56, v60
	v_cvt_pk_bf16_f32 v56, v56, v157
	ds_write_b16 v54, v56 offset:1088
	ds_read_u16 v56, v54 offset:1120
	v_mul_f32_e32 v55, v58, v55
	v_mul_f32_e32 v55, v99, v55
	s_waitcnt lgkmcnt(0)
	v_lshlrev_b32_e32 v56, 16, v56
	v_mul_f32_e32 v60, 0xbfb8aa3b, v56
	v_exp_f32_e32 v60, v60
	s_nop 0
	v_add_f32_e32 v60, 1.0, v60
	v_rcp_f32_e32 v60, v60
	s_nop 0
	v_mul_f32_e32 v56, v60, v56
	v_mul_f32_e32 v56, v56, v59
	v_cvt_pk_bf16_f32 v56, v56, v157
	ds_write_b16 v54, v56 offset:1120
	ds_read_u16 v56, v54 offset:1152
	v_mov_b32_e32 v60, v57
	s_waitcnt lgkmcnt(0)
	v_lshlrev_b32_e32 v56, 16, v56
	v_mul_f32_e32 v59, 0xbfb8aa3b, v56
	v_exp_f32_e32 v59, v59
	s_nop 0
	v_add_f32_e32 v59, 1.0, v59
	v_rcp_f32_e32 v59, v59
	s_nop 0
	v_mul_f32_e32 v56, v59, v56
	v_mul_f32_e32 v55, v55, v56
	v_cvt_pk_bf16_f32 v55, v55, v157
	v_pk_add_f32 v[58:59], v[60:61], v[68:69]
	ds_write_b16 v54, v55 offset:1152
	v_add_f32_e32 v55, v58, v59
	s_nop 1
	v_mov_b32_e32 v60, v69
	s_waitcnt lgkmcnt(0)
	v_add_f32_dpp v55, v55, v55 quad_perm:[1,0,3,2] row_mask:0xf bank_mask:0xf
	s_nop 1
	s_waitcnt lgkmcnt(0)
	v_add_f32_dpp v55, v55, v55 quad_perm:[2,3,0,1] row_mask:0xf bank_mask:0xf
	s_nop 1
	s_waitcnt lgkmcnt(0)
	v_add_f32_dpp v55, v55, v55 row_half_mirror row_mask:0xf bank_mask:0xf
	s_nop 1
	s_waitcnt lgkmcnt(0)
	v_add_f32_dpp v55, v55, v55 row_mirror row_mask:0xf bank_mask:0xf
	v_mul_f32_e32 v55, 0x3c800000, v55
	v_cndmask_b32_e32 v56, 0, v55, vcc
	v_pk_add_f32 v[58:59], v[64:65], v[56:57] op_sel_hi:[1,0] neg_lo:[0,1] neg_hi:[0,1]
	v_pk_add_f32 v[56:57], v[60:61], v[56:57] op_sel_hi:[1,0] neg_lo:[0,1] neg_hi:[0,1]
	v_pk_mul_f32 v[62:63], v[58:59], v[58:59]
	v_pk_mul_f32 v[60:61], v[56:57], v[56:57]
	v_add_f32_e32 v55, v62, v63
	v_add_f32_e32 v55, v61, v55
	v_add_f32_e32 v55, v60, v55
	s_nop 1
	v_lshlrev_b32_e32 v62, 16, v15
	v_and_b32_e32 v63, 0xffff0000, v15
	v_lshlrev_b32_e32 v64, 16, v16
	v_and_b32_e32 v65, 0xffff0000, v16
	s_waitcnt lgkmcnt(0)
	v_add_f32_dpp v55, v55, v55 quad_perm:[1,0,3,2] row_mask:0xf bank_mask:0xf
	s_nop 1
	s_waitcnt lgkmcnt(0)
	v_add_f32_dpp v55, v55, v55 quad_perm:[2,3,0,1] row_mask:0xf bank_mask:0xf
	s_nop 1
	s_waitcnt lgkmcnt(0)
	v_add_f32_dpp v55, v55, v55 row_half_mirror row_mask:0xf bank_mask:0xf
	s_nop 1
	s_waitcnt lgkmcnt(0)
	v_add_f32_dpp v55, v55, v55 row_mirror row_mask:0xf bank_mask:0xf
	v_fmamk_f32 v55, v55, 0x3c800000, v107
	v_cmp_gt_f32_e64 s[0:1], s3, v55
	v_mul_f32_e32 v60, 0x4b800000, v55
	s_nop 0
	v_cndmask_b32_e64 v55, v55, v60, s[0:1]
	v_rsq_f32_e32 v55, v55
	s_nop 0
	v_mul_f32_e32 v60, 0x45800000, v55
	v_cndmask_b32_e64 v55, v55, v60, s[0:1]
	ds_read_u16 v60, v54 offset:1584
	v_mul_f32_e32 v58, v58, v55
	v_mul_f32_e32 v58, v106, v58
	v_mul_f32_e32 v59, v59, v55
	v_mul_f32_e32 v59, v103, v59
	s_waitcnt lgkmcnt(0)
	v_lshlrev_b32_e32 v60, 16, v60
	v_mul_f32_e32 v61, 0xbfb8aa3b, v60
	v_exp_f32_e32 v61, v61
	v_mul_f32_e32 v57, v57, v55
	v_mul_f32_e32 v57, v101, v57
	v_mul_f32_e32 v55, v56, v55
	v_add_f32_e32 v61, 1.0, v61
	v_rcp_f32_e32 v61, v61
	v_mul_f32_e32 v55, v99, v55
	v_lshlrev_b32_e32 v56, 16, v18
	v_mul_f32_e32 v60, v61, v60
	v_mul_f32_e32 v58, v60, v58
	v_cvt_pk_bf16_f32 v58, v58, v157
	ds_write_b16 v54, v58 offset:1584
	ds_read_u16 v58, v54 offset:1616
	v_and_b32_e32 v61, 0xffff0000, v14
	s_waitcnt lgkmcnt(0)
	v_lshlrev_b32_e32 v58, 16, v58
	v_mul_f32_e32 v60, 0xbfb8aa3b, v58
	v_exp_f32_e32 v60, v60
	s_nop 0
	v_add_f32_e32 v60, 1.0, v60
	v_rcp_f32_e32 v60, v60
	s_nop 0
	v_mul_f32_e32 v58, v60, v58
	v_mul_f32_e32 v58, v58, v59
	v_cvt_pk_bf16_f32 v58, v58, v157
	ds_write_b16 v54, v58 offset:1616
	ds_read_u16 v58, v54 offset:1648
	v_lshlrev_b32_e32 v60, 16, v14
	s_waitcnt lgkmcnt(0)
	v_lshlrev_b32_e32 v58, 16, v58
	v_mul_f32_e32 v59, 0xbfb8aa3b, v58
	v_exp_f32_e32 v59, v59
	s_nop 0
	v_add_f32_e32 v59, 1.0, v59
	v_rcp_f32_e32 v59, v59
	s_nop 0
	v_mul_f32_e32 v58, v59, v58
	v_mul_f32_e32 v57, v58, v57
	v_cvt_pk_bf16_f32 v57, v57, v157
	ds_write_b16 v54, v57 offset:1648
	ds_read_u16 v57, v54 offset:1680
	v_and_b32_e32 v59, 0xffff0000, v19
	s_waitcnt lgkmcnt(0)
	v_lshlrev_b32_e32 v57, 16, v57
	v_mul_f32_e32 v58, 0xbfb8aa3b, v57
	v_exp_f32_e32 v58, v58
	s_nop 0
	v_add_f32_e32 v58, 1.0, v58
	v_rcp_f32_e32 v58, v58
	s_nop 0
	v_mul_f32_e32 v57, v58, v57
	v_mul_f32_e32 v55, v55, v57
	v_and_b32_e32 v57, 0xffff0000, v18
	v_lshlrev_b32_e32 v58, 16, v19
	v_lshlrev_b32_e32 v18, 16, v20
	v_and_b32_e32 v19, 0xffff0000, v20
	v_lshlrev_b32_e32 v20, 16, v21
	v_and_b32_e32 v21, 0xffff0000, v21
	v_mfma_f32_16x16x32_bf16 v[14:17], v[6:9], v[22:25], v[56:59]
	v_cvt_pk_bf16_f32 v55, v55, v157
	ds_write_b16 v54, v55 offset:1680
	v_mfma_f32_16x16x32_bf16 v[18:21], v[6:9], v[30:33], v[18:21]
	v_mfma_f32_16x16x32_bf16 v[22:25], v[10:13], v[34:37], v[18:21]
	v_mfma_f32_16x16x32_bf16 v[18:21], v[6:9], v[38:41], v[60:63]
	v_mfma_f32_16x16x32_bf16 v[6:9], v[6:9], v[46:49], v[64:67]
	v_mfma_f32_16x16x32_bf16 v[14:17], v[10:13], v[26:29], v[14:17]
	v_mfma_f32_16x16x32_bf16 v[18:21], v[10:13], v[42:45], v[18:21]
	v_mfma_f32_16x16x32_bf16 v[6:9], v[10:13], v[50:53], v[6:9]
	s_nop 5
	v_mov_b32_e32 v10, v14
	v_mov_b32_e32 v11, v18
	v_mov_b32_e32 v12, v22
	v_mov_b32_e32 v29, v18
	v_mov_b32_e32 v13, v6
	v_pk_add_f32 v[10:11], v[10:11], v[12:13]
	v_mov_b32_e32 v12, v14
	v_add_f32_e32 v10, v10, v11
	s_nop 1
	v_mov_b32_e32 v13, v22
	v_mov_b32_e32 v28, v6
	v_mov_b32_e32 v22, v15
	s_waitcnt lgkmcnt(0)
; #define LAS __attribute__((address_space(3)))
; __device__ __forceinline__ float bf2f(bf16_t b) { return __uint_as_float((unsigned)b << 16); }
; __device__ __forceinline__ bf16_t f2bf(float f) { return (bf16_t)(pk2(f, 0.f) & 0xffffu); }
; __device__ __forceinline__ float silu_acc(float x) { return x * frcp(1.0f + fexp(-x)); }
; __device__ __forceinline__ void mixer_out_phase(const Ctx& X, LAS unsigned char* lds, int layer, int tid, int wave, int lane) {
;     ...
; #pragma unroll
;             for (int j = 0; j < 4; ++j) {
;                 float sm = (acc[0][j] + acc[1][j]) + (acc[2][j] + acc[3][j]);
;                 sm += __shfl_xor(sm, 1); sm += __shfl_xor(sm, 2); sm += __shfl_xor(sm, 4); sm += __shfl_xor(sm, 8);
;                 const float mu = mixer == 0 ? sm * (1.f / 64.f) : 0.f;
;                 float d[4], s2 = 0.f;
; #pragma unroll
;                 for (int ct = 0; ct < 4; ++ct) { d[ct] = acc[ct][j] - mu; s2 += d[ct] * d[ct]; }
;                 s2 += __shfl_xor(s2, 1); s2 += __shfl_xor(s2, 2); s2 += __shfl_xor(s2, 4); s2 += __shfl_xor(s2, 8);
;                 const float rs = rsqrtf(s2 * (1.f / 64.f) + (mixer == 0 ? 1e-5f : 1e-6f));
;                 const int ii = 16 * (2 * half + rt) + 4 * q + j;
; #pragma unroll
;                 for (int ct = 0; ct < 4; ++ct) { LAS bf16_t* gp = GT + ii * GP + h * 64 + 16 * ct + r;
;                     const float y = d[ct] * rs * wv[ct] * silu_acc(bf2f(*gp));
;                     *gp = on ? f2bf(y) : (bf16_t)0; }
	v_add_f32_dpp v10, v10, v10 quad_perm:[1,0,3,2] row_mask:0xf bank_mask:0xf
	s_nop 1
	s_waitcnt lgkmcnt(0)
	v_add_f32_dpp v10, v10, v10 quad_perm:[2,3,0,1] row_mask:0xf bank_mask:0xf
	s_nop 1
	s_waitcnt lgkmcnt(0)
	v_add_f32_dpp v10, v10, v10 row_half_mirror row_mask:0xf bank_mask:0xf
	s_nop 1
	s_waitcnt lgkmcnt(0)
	v_add_f32_dpp v10, v10, v10 row_mirror row_mask:0xf bank_mask:0xf
	v_mul_f32_e32 v10, 0x3c800000, v10
	v_cndmask_b32_e32 v10, 0, v10, vcc
	v_pk_add_f32 v[12:13], v[12:13], v[10:11] op_sel_hi:[1,0] neg_lo:[0,1] neg_hi:[0,1]
	v_pk_add_f32 v[10:11], v[28:29], v[10:11] op_sel_hi:[1,0] neg_lo:[0,1] neg_hi:[0,1]
	v_pk_mul_f32 v[26:27], v[12:13], v[12:13]
	v_pk_mul_f32 v[28:29], v[10:11], v[10:11]
	v_add_f32_e32 v6, v26, v27
	v_add_f32_e32 v6, v29, v6
	v_add_f32_e32 v6, v28, v6
	s_nop 1
	s_waitcnt lgkmcnt(0)
	v_add_f32_dpp v6, v6, v6 quad_perm:[1,0,3,2] row_mask:0xf bank_mask:0xf
	s_nop 1
	s_waitcnt lgkmcnt(0)
	v_add_f32_dpp v6, v6, v6 quad_perm:[2,3,0,1] row_mask:0xf bank_mask:0xf
	s_nop 1
	s_waitcnt lgkmcnt(0)
	v_add_f32_dpp v6, v6, v6 row_half_mirror row_mask:0xf bank_mask:0xf
	s_nop 1
	s_waitcnt lgkmcnt(0)
	v_add_f32_dpp v6, v6, v6 row_mirror row_mask:0xf bank_mask:0xf
	v_fmamk_f32 v6, v6, 0x3c800000, v107
	v_cmp_gt_f32_e64 s[0:1], s3, v6
	v_mul_f32_e32 v14, 0x4b800000, v6
	s_nop 0
	v_cndmask_b32_e64 v6, v6, v14, s[0:1]
	v_rsq_f32_e32 v6, v6
	s_nop 0
	v_mul_f32_e32 v14, 0x45800000, v6
	v_cndmask_b32_e64 v6, v6, v14, s[0:1]
	ds_read_u16 v14, v54 offset:8448
	v_mul_f32_e32 v12, v12, v6
	v_mul_f32_e32 v12, v106, v12
	v_mul_f32_e32 v13, v13, v6
	v_mul_f32_e32 v13, v103, v13
	s_waitcnt lgkmcnt(0)
	v_lshlrev_b32_e32 v14, 16, v14
	v_mul_f32_e32 v18, 0xbfb8aa3b, v14
	v_exp_f32_e32 v18, v18
	v_mul_f32_e32 v11, v11, v6
	v_mul_f32_e32 v11, v101, v11
	v_mul_f32_e32 v6, v10, v6
	v_add_f32_e32 v18, 1.0, v18
	v_rcp_f32_e32 v18, v18
	v_mul_f32_e32 v6, v99, v6
	v_mul_f32_e32 v14, v18, v14
	v_mul_f32_e32 v12, v14, v12
	v_cvt_pk_bf16_f32 v12, v12, v157
	ds_write_b16 v54, v12 offset:8448
	ds_read_u16 v12, v54 offset:8480
	v_mov_b32_e32 v18, v15
	s_waitcnt lgkmcnt(0)
	v_lshlrev_b32_e32 v12, 16, v12
	v_mul_f32_e32 v14, 0xbfb8aa3b, v12
	v_exp_f32_e32 v14, v14
	s_nop 0
	v_add_f32_e32 v14, 1.0, v14
	v_rcp_f32_e32 v14, v14
	s_nop 0
	v_mul_f32_e32 v12, v14, v12
	v_mul_f32_e32 v12, v12, v13
	v_cvt_pk_bf16_f32 v12, v12, v157
	ds_write_b16 v54, v12 offset:8480
	ds_read_u16 v12, v54 offset:8512
	s_waitcnt lgkmcnt(0)
	v_lshlrev_b32_e32 v12, 16, v12
	v_mul_f32_e32 v13, 0xbfb8aa3b, v12
	v_exp_f32_e32 v13, v13
	s_nop 0
	v_add_f32_e32 v13, 1.0, v13
	v_rcp_f32_e32 v13, v13
	s_nop 0
	v_mul_f32_e32 v12, v13, v12
	v_mul_f32_e32 v11, v12, v11
	v_cvt_pk_bf16_f32 v11, v11, v157
	ds_write_b16 v54, v11 offset:8512
	ds_read_u16 v11, v54 offset:8544
	s_waitcnt lgkmcnt(0)
	v_lshlrev_b32_e32 v11, 16, v11
	v_mul_f32_e32 v12, 0xbfb8aa3b, v11
	v_exp_f32_e32 v12, v12
	s_nop 0
	v_add_f32_e32 v12, 1.0, v12
	v_rcp_f32_e32 v12, v12
	s_nop 0
	v_mul_f32_e32 v11, v12, v11
	v_mul_f32_e32 v6, v11, v6
	v_cvt_pk_bf16_f32 v6, v6, v157
	ds_write_b16 v54, v6 offset:8544
	v_mov_b32_e32 v6, v23
	v_pk_add_f32 v[10:11], v[18:19], v[6:7]
	v_mov_b32_e32 v18, v7
	v_add_f32_e32 v6, v10, v11
	s_nop 1
	s_waitcnt lgkmcnt(0)
	v_add_f32_dpp v6, v6, v6 quad_perm:[1,0,3,2] row_mask:0xf bank_mask:0xf
	s_nop 1
	s_waitcnt lgkmcnt(0)
	v_add_f32_dpp v6, v6, v6 quad_perm:[2,3,0,1] row_mask:0xf bank_mask:0xf
	s_nop 1
	s_waitcnt lgkmcnt(0)
	v_add_f32_dpp v6, v6, v6 row_half_mirror row_mask:0xf bank_mask:0xf
	s_nop 1
	s_waitcnt lgkmcnt(0)
	v_add_f32_dpp v6, v6, v6 row_mirror row_mask:0xf bank_mask:0xf
	v_mul_f32_e32 v6, 0x3c800000, v6
	v_cndmask_b32_e32 v6, 0, v6, vcc
	v_pk_add_f32 v[10:11], v[22:23], v[6:7] op_sel_hi:[1,0] neg_lo:[0,1] neg_hi:[0,1]
	v_pk_add_f32 v[6:7], v[18:19], v[6:7] op_sel_hi:[1,0] neg_lo:[0,1] neg_hi:[0,1]
	v_pk_mul_f32 v[12:13], v[10:11], v[10:11]
	v_pk_mul_f32 v[14:15], v[6:7], v[6:7]
	v_add_f32_e32 v12, v12, v13
	v_add_f32_e32 v12, v15, v12
	v_add_f32_e32 v12, v14, v12
	s_nop 1
	v_mov_b32_e32 v15, v20
	s_waitcnt lgkmcnt(0)
	v_add_f32_dpp v12, v12, v12 quad_perm:[1,0,3,2] row_mask:0xf bank_mask:0xf
	s_nop 1
	s_waitcnt lgkmcnt(0)
	v_add_f32_dpp v12, v12, v12 quad_perm:[2,3,0,1] row_mask:0xf bank_mask:0xf
	s_nop 1
	s_waitcnt lgkmcnt(0)
	v_add_f32_dpp v12, v12, v12 row_half_mirror row_mask:0xf bank_mask:0xf
	s_nop 1
	s_waitcnt lgkmcnt(0)
	v_add_f32_dpp v12, v12, v12 row_mirror row_mask:0xf bank_mask:0xf
	v_fmamk_f32 v12, v12, 0x3c800000, v107
	v_cmp_gt_f32_e64 s[0:1], s3, v12
	v_mul_f32_e32 v13, 0x4b800000, v12
	s_nop 0
	v_cndmask_b32_e64 v12, v12, v13, s[0:1]
	v_rsq_f32_e32 v12, v12
	s_nop 0
	v_mul_f32_e32 v13, 0x45800000, v12
	v_cndmask_b32_e64 v12, v12, v13, s[0:1]
	ds_read_u16 v13, v54 offset:8976
	v_mul_f32_e32 v10, v10, v12
	v_mul_f32_e32 v10, v106, v10
	v_mul_f32_e32 v11, v11, v12
	v_mul_f32_e32 v11, v103, v11
	s_waitcnt lgkmcnt(0)
	v_lshlrev_b32_e32 v13, 16, v13
	v_mul_f32_e32 v14, 0xbfb8aa3b, v13
	v_exp_f32_e32 v14, v14
	v_mul_f32_e32 v7, v7, v12
	v_mul_f32_e32 v7, v101, v7
	v_mul_f32_e32 v6, v6, v12
	v_add_f32_e32 v14, 1.0, v14
	v_rcp_f32_e32 v14, v14
	v_mul_f32_e32 v6, v99, v6
	v_mul_f32_e32 v13, v14, v13
	v_mul_f32_e32 v10, v13, v10
	v_cvt_pk_bf16_f32 v10, v10, v157
	ds_write_b16 v54, v10 offset:8976
	ds_read_u16 v10, v54 offset:9008
	v_mov_b32_e32 v14, v8
	s_waitcnt lgkmcnt(0)
	v_lshlrev_b32_e32 v10, 16, v10
	v_mul_f32_e32 v13, 0xbfb8aa3b, v10
	v_exp_f32_e32 v13, v13
	s_nop 0
	v_add_f32_e32 v13, 1.0, v13
	v_rcp_f32_e32 v13, v13
	s_nop 0
	v_mul_f32_e32 v10, v13, v10
	v_mul_f32_e32 v10, v10, v11
	v_cvt_pk_bf16_f32 v10, v10, v157
	ds_write_b16 v54, v10 offset:9008
	ds_read_u16 v10, v54 offset:9040
	s_waitcnt lgkmcnt(0)
; #define LAS __attribute__((address_space(3)))
; __device__ __forceinline__ float bf2f(bf16_t b) { return __uint_as_float((unsigned)b << 16); }
; __device__ __forceinline__ bf16_t f2bf(float f) { return (bf16_t)(pk2(f, 0.f) & 0xffffu); }
; __device__ __forceinline__ float silu_acc(float x) { return x * frcp(1.0f + fexp(-x)); }
; __device__ __forceinline__ void mixer_out_phase(const Ctx& X, LAS unsigned char* lds, int layer, int tid, int wave, int lane) {
;     ...
; #pragma unroll
;             for (int j = 0; j < 4; ++j) {
;                 float sm = (acc[0][j] + acc[1][j]) + (acc[2][j] + acc[3][j]);
;                 sm += __shfl_xor(sm, 1); sm += __shfl_xor(sm, 2); sm += __shfl_xor(sm, 4); sm += __shfl_xor(sm, 8);
;                 const float mu = mixer == 0 ? sm * (1.f / 64.f) : 0.f;
;                 float d[4], s2 = 0.f;
; #pragma unroll
;                 for (int ct = 0; ct < 4; ++ct) { d[ct] = acc[ct][j] - mu; s2 += d[ct] * d[ct]; }
;                 s2 += __shfl_xor(s2, 1); s2 += __shfl_xor(s2, 2); s2 += __shfl_xor(s2, 4); s2 += __shfl_xor(s2, 8);
;                 const float rs = rsqrtf(s2 * (1.f / 64.f) + (mixer == 0 ? 1e-5f : 1e-6f));
;                 const int ii = 16 * (2 * half + rt) + 4 * q + j;
; #pragma unroll
;                 for (int ct = 0; ct < 4; ++ct) { LAS bf16_t* gp = GT + ii * GP + h * 64 + 16 * ct + r;
;                     const float y = d[ct] * rs * wv[ct] * silu_acc(bf2f(*gp));
;                     *gp = on ? f2bf(y) : (bf16_t)0; }
	v_lshlrev_b32_e32 v10, 16, v10
	v_mul_f32_e32 v11, 0xbfb8aa3b, v10
	v_exp_f32_e32 v11, v11
	s_nop 0
	v_add_f32_e32 v11, 1.0, v11
	v_rcp_f32_e32 v11, v11
	s_nop 0
	v_mul_f32_e32 v10, v11, v10
	v_mul_f32_e32 v7, v10, v7
	v_cvt_pk_bf16_f32 v7, v7, v157
	ds_write_b16 v54, v7 offset:9040
	ds_read_u16 v7, v54 offset:9072
	v_mov_b32_e32 v11, v8
	s_waitcnt lgkmcnt(0)
	v_lshlrev_b32_e32 v7, 16, v7
	v_mul_f32_e32 v10, 0xbfb8aa3b, v7
	v_exp_f32_e32 v10, v10
	s_nop 0
	v_add_f32_e32 v10, 1.0, v10
	v_rcp_f32_e32 v10, v10
	s_nop 0
	v_mul_f32_e32 v7, v10, v7
	v_mul_f32_e32 v6, v6, v7
	v_cvt_pk_bf16_f32 v6, v6, v157
	ds_write_b16 v54, v6 offset:9072
	v_mov_b32_e32 v6, v16
	v_mov_b32_e32 v7, v20
	v_mov_b32_e32 v10, v24
	v_pk_add_f32 v[6:7], v[6:7], v[10:11]
	v_mov_b32_e32 v10, v16
	v_add_f32_e32 v6, v6, v7
	s_nop 1
	v_mov_b32_e32 v11, v24
	v_mov_b32_e32 v20, v17
	v_mov_b32_e32 v24, v17
	s_waitcnt lgkmcnt(0)
	v_add_f32_dpp v6, v6, v6 quad_perm:[1,0,3,2] row_mask:0xf bank_mask:0xf
	s_nop 1
	s_waitcnt lgkmcnt(0)
	v_add_f32_dpp v6, v6, v6 quad_perm:[2,3,0,1] row_mask:0xf bank_mask:0xf
	s_nop 1
	s_waitcnt lgkmcnt(0)
	v_add_f32_dpp v6, v6, v6 row_half_mirror row_mask:0xf bank_mask:0xf
	s_nop 1
	s_waitcnt lgkmcnt(0)
	v_add_f32_dpp v6, v6, v6 row_mirror row_mask:0xf bank_mask:0xf
	v_mul_f32_e32 v6, 0x3c800000, v6
	v_cndmask_b32_e32 v6, 0, v6, vcc
	v_pk_add_f32 v[10:11], v[10:11], v[6:7] op_sel_hi:[1,0] neg_lo:[0,1] neg_hi:[0,1]
	v_pk_add_f32 v[6:7], v[14:15], v[6:7] op_sel_hi:[1,0] neg_lo:[0,1] neg_hi:[0,1]
	v_pk_mul_f32 v[12:13], v[10:11], v[10:11]
	v_pk_mul_f32 v[14:15], v[6:7], v[6:7]
	v_add_f32_e32 v8, v12, v13
	v_add_f32_e32 v8, v15, v8
	v_add_f32_e32 v8, v14, v8
	s_nop 1
	s_waitcnt lgkmcnt(0)
	v_add_f32_dpp v8, v8, v8 quad_perm:[1,0,3,2] row_mask:0xf bank_mask:0xf
	s_nop 1
	s_waitcnt lgkmcnt(0)
	v_add_f32_dpp v8, v8, v8 quad_perm:[2,3,0,1] row_mask:0xf bank_mask:0xf
	s_nop 1
	s_waitcnt lgkmcnt(0)
	v_add_f32_dpp v8, v8, v8 row_half_mirror row_mask:0xf bank_mask:0xf
	s_nop 1
	s_waitcnt lgkmcnt(0)
	v_add_f32_dpp v8, v8, v8 row_mirror row_mask:0xf bank_mask:0xf
	v_fmamk_f32 v8, v8, 0x3c800000, v107
	v_cmp_gt_f32_e64 s[0:1], s3, v8
	v_mul_f32_e32 v12, 0x4b800000, v8
	s_nop 0
	v_cndmask_b32_e64 v8, v8, v12, s[0:1]
	v_rsq_f32_e32 v8, v8
	s_nop 0
	v_mul_f32_e32 v12, 0x45800000, v8
	v_cndmask_b32_e64 v8, v8, v12, s[0:1]
	ds_read_u16 v12, v54 offset:9504
	v_mul_f32_e32 v10, v10, v8
	v_mul_f32_e32 v10, v106, v10
	v_mul_f32_e32 v11, v11, v8
	v_mul_f32_e32 v11, v103, v11
	s_waitcnt lgkmcnt(0)
	v_lshlrev_b32_e32 v12, 16, v12
	v_mul_f32_e32 v13, 0xbfb8aa3b, v12
	v_exp_f32_e32 v13, v13
	v_mul_f32_e32 v7, v7, v8
	v_mul_f32_e32 v7, v101, v7
	v_mul_f32_e32 v6, v6, v8
	v_add_f32_e32 v13, 1.0, v13
	v_rcp_f32_e32 v13, v13
	v_mul_f32_e32 v6, v99, v6
	v_mov_b32_e32 v8, v25
	s_lshl_b32 s0, s11, 1
	v_mul_f32_e32 v12, v13, v12
	v_mul_f32_e32 v10, v12, v10
	v_cvt_pk_bf16_f32 v10, v10, v157
	ds_write_b16 v54, v10 offset:9504
	ds_read_u16 v10, v54 offset:9536
	s_add_u32 s0, s60, s0
	s_addc_u32 s1, s67, 0
	s_add_i32 s10, s10, s18
	s_cmpk_lt_i32 s10, 0x600
	s_waitcnt lgkmcnt(0)
	v_lshlrev_b32_e32 v10, 16, v10
	v_mul_f32_e32 v12, 0xbfb8aa3b, v10
	v_exp_f32_e32 v12, v12
	s_nop 0
	v_add_f32_e32 v12, 1.0, v12
	v_rcp_f32_e32 v12, v12
	s_nop 0
	v_mul_f32_e32 v10, v12, v10
	v_mul_f32_e32 v10, v10, v11
	v_cvt_pk_bf16_f32 v10, v10, v157
	ds_write_b16 v54, v10 offset:9536
	ds_read_u16 v10, v54 offset:9568
	s_waitcnt lgkmcnt(0)
	v_lshlrev_b32_e32 v10, 16, v10
	v_mul_f32_e32 v11, 0xbfb8aa3b, v10
	v_exp_f32_e32 v11, v11
	s_nop 0
	v_add_f32_e32 v11, 1.0, v11
	v_rcp_f32_e32 v11, v11
	s_nop 0
	v_mul_f32_e32 v10, v11, v10
	v_mul_f32_e32 v7, v10, v7
	v_cvt_pk_bf16_f32 v7, v7, v157
	ds_write_b16 v54, v7 offset:9568
	ds_read_u16 v7, v54 offset:9600
	s_waitcnt lgkmcnt(0)
	v_lshlrev_b32_e32 v7, 16, v7
	v_mul_f32_e32 v10, 0xbfb8aa3b, v7
	v_exp_f32_e32 v10, v10
	s_nop 0
	v_add_f32_e32 v10, 1.0, v10
	v_rcp_f32_e32 v10, v10
	s_nop 0
	v_mul_f32_e32 v7, v10, v7
	v_mul_f32_e32 v6, v6, v7
	v_cvt_pk_bf16_f32 v6, v6, v157
	ds_write_b16 v54, v6 offset:9600
	v_pk_add_f32 v[6:7], v[20:21], v[8:9]
	v_mov_b32_e32 v20, v9
	v_add_f32_e32 v6, v6, v7
	s_nop 1
	s_waitcnt lgkmcnt(0)
; #define LAS __attribute__((address_space(3)))
; __device__ __forceinline__ float bf2f(bf16_t b) { return __uint_as_float((unsigned)b << 16); }
; __device__ __forceinline__ bf16_t f2bf(float f) { return (bf16_t)(pk2(f, 0.f) & 0xffffu); }
; __device__ __forceinline__ float silu_acc(float x) { return x * frcp(1.0f + fexp(-x)); }
; #define LBAR() do { asm volatile("s_waitcnt lgkmcnt(0)" ::: "memory"); __builtin_amdgcn_s_barrier(); asm volatile("" ::: "memory"); } while (0)
; __device__ __forceinline__ void mixer_out_phase(const Ctx& X, LAS unsigned char* lds, int layer, int tid, int wave, int lane) {
;     ...
; #pragma unroll
;             for (int j = 0; j < 4; ++j) {
;                 float sm = (acc[0][j] + acc[1][j]) + (acc[2][j] + acc[3][j]);
;                 sm += __shfl_xor(sm, 1); sm += __shfl_xor(sm, 2); sm += __shfl_xor(sm, 4); sm += __shfl_xor(sm, 8);
;                 const float mu = mixer == 0 ? sm * (1.f / 64.f) : 0.f;
;                 float d[4], s2 = 0.f;
; #pragma unroll
;                 for (int ct = 0; ct < 4; ++ct) { d[ct] = acc[ct][j] - mu; s2 += d[ct] * d[ct]; }
;                 s2 += __shfl_xor(s2, 1); s2 += __shfl_xor(s2, 2); s2 += __shfl_xor(s2, 4); s2 += __shfl_xor(s2, 8);
;                 const float rs = rsqrtf(s2 * (1.f / 64.f) + (mixer == 0 ? 1e-5f : 1e-6f));
;                 const int ii = 16 * (2 * half + rt) + 4 * q + j;
; #pragma unroll
;                 for (int ct = 0; ct < 4; ++ct) { LAS bf16_t* gp = GT + ii * GP + h * 64 + 16 * ct + r;
;                     const float y = d[ct] * rs * wv[ct] * silu_acc(bf2f(*gp));
;                     *gp = on ? f2bf(y) : (bf16_t)0; }
;             }
;         }
;         LBAR();
; #pragma unroll
;         for (int n = 0; n < 4; ++n) { const int idx = tid + 512 * n; __builtin_nontemporal_store(*(const LAS u32x4*)(GT + (idx >> 5) * GP + (idx & 31) * 8), (u32x4*)(mix + (row0 + (idx >> 5)) * D + moff + (idx & 31) * 8)); }
;         LBAR();
	v_add_f32_dpp v6, v6, v6 quad_perm:[1,0,3,2] row_mask:0xf bank_mask:0xf
	s_nop 1
	s_waitcnt lgkmcnt(0)
	v_add_f32_dpp v6, v6, v6 quad_perm:[2,3,0,1] row_mask:0xf bank_mask:0xf
	s_nop 1
	s_waitcnt lgkmcnt(0)
	v_add_f32_dpp v6, v6, v6 row_half_mirror row_mask:0xf bank_mask:0xf
	s_nop 1
	s_waitcnt lgkmcnt(0)
	v_add_f32_dpp v6, v6, v6 row_mirror row_mask:0xf bank_mask:0xf
	v_mul_f32_e32 v6, 0x3c800000, v6
	v_cndmask_b32_e32 v6, 0, v6, vcc
	v_pk_add_f32 v[10:11], v[24:25], v[6:7] op_sel_hi:[1,0] neg_lo:[0,1] neg_hi:[0,1]
	v_pk_add_f32 v[6:7], v[20:21], v[6:7] op_sel_hi:[1,0] neg_lo:[0,1] neg_hi:[0,1]
	v_pk_mul_f32 v[12:13], v[10:11], v[10:11]
	v_pk_mul_f32 v[8:9], v[6:7], v[6:7]
	v_add_f32_e32 v12, v12, v13
	v_add_f32_e32 v9, v9, v12
	v_add_f32_e32 v8, v8, v9
	s_nop 1
	s_waitcnt lgkmcnt(0)
	v_add_f32_dpp v8, v8, v8 quad_perm:[1,0,3,2] row_mask:0xf bank_mask:0xf
	s_nop 1
	s_waitcnt lgkmcnt(0)
	v_add_f32_dpp v8, v8, v8 quad_perm:[2,3,0,1] row_mask:0xf bank_mask:0xf
	s_nop 1
	s_waitcnt lgkmcnt(0)
	v_add_f32_dpp v8, v8, v8 row_half_mirror row_mask:0xf bank_mask:0xf
	s_nop 1
	s_waitcnt lgkmcnt(0)
	v_add_f32_dpp v8, v8, v8 row_mirror row_mask:0xf bank_mask:0xf
	v_fmac_f32_e32 v107, 0x3c800000, v8
	v_cmp_gt_f32_e32 vcc, s3, v107
	v_mul_f32_e32 v8, 0x4b800000, v107
	s_nop 0
	v_cndmask_b32_e32 v8, v107, v8, vcc
	v_rsq_f32_e32 v8, v8
	s_nop 0
	v_mul_f32_e32 v9, 0x45800000, v8
	v_cndmask_b32_e32 v8, v8, v9, vcc
	ds_read_u16 v9, v54 offset:10032
	v_mul_f32_e32 v10, v10, v8
	v_mul_f32_e32 v10, v106, v10
	v_mul_f32_e32 v7, v7, v8
	v_mul_f32_e32 v7, v101, v7
	s_waitcnt lgkmcnt(0)
	v_lshlrev_b32_e32 v9, 16, v9
	v_mul_f32_e32 v12, 0xbfb8aa3b, v9
	v_exp_f32_e32 v12, v12
	v_mul_f32_e32 v6, v6, v8
	v_mul_f32_e32 v6, v99, v6
	v_add_f32_e32 v12, 1.0, v12
	v_rcp_f32_e32 v12, v12
	s_nop 0
	v_mul_f32_e32 v9, v12, v9
	v_mul_f32_e32 v9, v9, v10
	v_cvt_pk_bf16_f32 v9, v9, v157
	ds_write_b16 v54, v9 offset:10032
	ds_read_u16 v9, v54 offset:10064
	v_lshlrev_b64 v[12:13], 11, v[92:93]
	s_waitcnt lgkmcnt(0)
	v_lshlrev_b32_e32 v9, 16, v9
	v_mul_f32_e32 v10, 0xbfb8aa3b, v9
	v_exp_f32_e32 v10, v10
	s_nop 0
	v_add_f32_e32 v10, 1.0, v10
	v_rcp_f32_e32 v10, v10
	s_nop 0
	v_mul_f32_e32 v9, v10, v9
	v_mul_f32_e32 v10, v11, v8
	v_mul_f32_e32 v10, v103, v10
	v_mul_f32_e32 v9, v9, v10
	v_cvt_pk_bf16_f32 v9, v9, v157
	ds_write_b16 v54, v9 offset:10064
	ds_read_u16 v9, v54 offset:10096
	s_waitcnt lgkmcnt(0)
	v_lshlrev_b32_e32 v9, 16, v9
	v_mul_f32_e32 v10, 0xbfb8aa3b, v9
	v_exp_f32_e32 v10, v10
	s_nop 0
	v_add_f32_e32 v10, 1.0, v10
	v_rcp_f32_e32 v10, v10
	s_nop 0
	v_mul_f32_e32 v9, v10, v9
	v_mul_f32_e32 v7, v9, v7
	v_cvt_pk_bf16_f32 v7, v7, v157
	ds_write_b16 v54, v7 offset:10096
	ds_read_u16 v7, v54 offset:10128
	v_lshl_add_u64 v[10:11], s[0:1], 0, v[156:157]
	v_lshl_add_u64 v[12:13], v[10:11], 0, v[12:13]
	s_waitcnt lgkmcnt(0)
	v_lshlrev_b32_e32 v7, 16, v7
	v_mul_f32_e32 v9, 0xbfb8aa3b, v7
	v_exp_f32_e32 v9, v9
	s_nop 0
	v_add_f32_e32 v9, 1.0, v9
	v_rcp_f32_e32 v9, v9
	s_nop 0
	v_mul_f32_e32 v7, v9, v7
	v_mul_f32_e32 v6, v6, v7
	v_cvt_pk_bf16_f32 v6, v6, v157
	ds_write_b16 v54, v6 offset:10128
	s_waitcnt lgkmcnt(0)
	s_barrier
	ds_read_b128 v[6:9], v96
	s_waitcnt lgkmcnt(0)
	global_store_dwordx4 v[12:13], v[6:9], off nt
	ds_read_b128 v[6:9], v94
	v_lshlrev_b64 v[12:13], 11, v[90:91]
	v_lshl_add_u64 v[12:13], v[10:11], 0, v[12:13]
	s_waitcnt lgkmcnt(0)
	global_store_dwordx4 v[12:13], v[6:9], off nt
	ds_read_b128 v[6:9], v76
	v_lshlrev_b64 v[12:13], 11, v[88:89]
	v_lshl_add_u64 v[12:13], v[10:11], 0, v[12:13]
	s_waitcnt lgkmcnt(0)
	global_store_dwordx4 v[12:13], v[6:9], off nt
	ds_read_b128 v[6:9], v74
	v_lshlrev_b64 v[12:13], 11, v[86:87]
	v_lshl_add_u64 v[10:11], v[10:11], 0, v[12:13]
	s_waitcnt lgkmcnt(0)
	global_store_dwordx4 v[10:11], v[6:9], off nt
	s_waitcnt lgkmcnt(0)
	s_barrier
	s_cbranch_scc1 .LBB0_888
	v_readlane_b32 s54, v255, 7
	v_readlane_b32 s56, v255, 9
	v_readlane_b32 s58, v255, 11
	v_readlane_b32 s48, v255, 13
	v_readlane_b32 s50, v255, 15
	v_readlane_b32 s52, v255, 17
	v_readlane_b32 s55, v255, 8
	v_readlane_b32 s57, v255, 10
	v_readlane_b32 s59, v255, 12
	v_readlane_b32 s49, v255, 14
	v_readlane_b32 s51, v255, 16
	v_readlane_b32 s53, v255, 18
	s_mov_b64 s[22:23], s[64:65]
	v_readlane_b32 s19, v255, 26
